# attention unit start: the 4 serial KX-table load->wait->ds_write round trips issued as one batch with counted vmcnt
# speedup vs baseline: 1.0182x; 1.0046x over previous
; #define LAS __attribute__((address_space(3)))
; #define KARG(i) ({ unsigned long long p_; asm volatile("s_load_dwordx2 %0, %1, %2\n\ts_waitcnt lgkmcnt(0)" : "=s"(p_) : "s"((unsigned long long)__builtin_amdgcn_kernarg_segment_ptr()), "n"((i) * 8)); p_; })
; __global__ void __launch_bounds__(NWAVES * 64, 2) mk_fwd(Args args) {
;     ...
;             {
;                 LAS v4u* kxt = (LAS v4u*)(lds + attn_body::LDS_KX); const v4u* src = (const v4u*)((const unsigned char*)KARG(20) + WS_KXG) + (size_t)bh * SEQ;
; #pragma unroll
;                 for (int j = 0; j < 4; ++j) kxt[tid + 512 * j] = src[tid + 512 * j];
;                 if (tid == 0) { unsigned zz = 0u; asm volatile("" : "+v"(zz)); kxt[SEQ] = (v4u){zz, zz, zz, zz}; }
;                 __syncthreads();
.LBB0_238:
	s_ashr_i32 s6, s85, 1
	s_ashr_i32 s7, s6, 31
	s_load_dwordx2 s[8:9], s[0:1], 0xa0
	s_waitcnt lgkmcnt(0)
	s_lshl_b64 s[34:35], s[6:7], 15
	s_add_u32 s8, s8, s34
	s_addc_u32 s9, s9, s35
	v_lshl_add_u64 v[4:5], v[200:201], 4, s[8:9]
	v_add_co_u32_e32 v0, vcc, 0x1c800000, v4
	s_nop 1
	v_addc_co_u32_e32 v1, vcc, 0, v5, vcc
	global_load_dwordx4 v[100:103], v[0:1], off
	v_add_co_u32_e32 v6, vcc, 0x1c802000, v4
	s_nop 1
	v_addc_co_u32_e32 v7, vcc, 0, v5, vcc
	global_load_dwordx4 v[104:107], v[6:7], off
	v_add_co_u32_e32 v6, vcc, 0x1c804000, v4
	s_nop 1
	v_addc_co_u32_e32 v7, vcc, 0, v5, vcc
	global_load_dwordx4 v[108:111], v[6:7], off
	v_add_co_u32_e32 v4, vcc, 0x1c806000, v4
	s_nop 1
	v_addc_co_u32_e32 v5, vcc, 0, v5, vcc
	global_load_dwordx4 v[0:3], v[4:5], off
	s_waitcnt vmcnt(3) lgkmcnt(0)
	ds_write_b128 v221, v[100:103]
	s_waitcnt vmcnt(2)
	ds_write_b128 v222, v[104:107]
	s_waitcnt vmcnt(1)
	ds_write_b128 v223, v[108:111]
	s_waitcnt vmcnt(0)
	ds_write_b128 v224, v[0:3]
	s_and_saveexec_b64 s[8:9], s[4:5]
	s_cbranch_execz .LBB0_240
	v_mov_b32_e32 v0, v99
	v_mov_b32_e32 v4, s83
	v_mov_b32_e32 v1, v0
	v_mov_b32_e32 v2, v0
	v_mov_b32_e32 v3, v0
	ds_write_b128 v4, v[0:3]
